# v15 with 7 V^T fragments in flight in the PV section (was 4), extra buffers v[242:253]
# baseline (speedup 1.0000x reference)
.LBB0_1410:
	s_lshl_b32 s0, s70, 14
	s_add_i32 s0, s0, 0
	s_add_i32 s0, s0, 0x12000
	v_add_u32_e32 v16, s0, v163
	v_add_u32_e32 v17, s0, v212
	ds_read_b64_tr_b16 v[226:227], v16 offset:0
	ds_read_b64_tr_b16 v[228:229], v16 offset:2048
	ds_read_b64_tr_b16 v[230:231], v17 offset:0
	ds_read_b64_tr_b16 v[232:233], v17 offset:2048
	ds_read_b64_tr_b16 v[234:235], v16 offset:1024
	ds_read_b64_tr_b16 v[236:237], v16 offset:3072
	ds_read_b64_tr_b16 v[238:239], v17 offset:1024
	ds_read_b64_tr_b16 v[240:241], v17 offset:3072
	ds_read_b64_tr_b16 v[242:243], v16 offset:4096
	ds_read_b64_tr_b16 v[244:245], v16 offset:6144
	ds_read_b64_tr_b16 v[246:247], v17 offset:4096
	ds_read_b64_tr_b16 v[248:249], v17 offset:6144
	ds_read_b64_tr_b16 v[250:251], v16 offset:5120
	ds_read_b64_tr_b16 v[252:253], v16 offset:7168
	v_exp_f32_e32 v34, v34
	v_exp_f32_e32 v35, v35
	v_add_f32_e32 v220, v220, v34
	v_add_f32_e32 v220, v220, v35
	v_exp_f32_e32 v36, v36
	v_exp_f32_e32 v37, v37
	v_add_f32_e32 v220, v220, v36
	v_add_f32_e32 v220, v220, v37
	v_exp_f32_e32 v38, v38
	v_exp_f32_e32 v39, v39
	v_add_f32_e32 v220, v220, v38
	v_add_f32_e32 v220, v220, v39
	v_exp_f32_e32 v40, v40
	v_exp_f32_e32 v41, v41
	v_add_f32_e32 v220, v220, v40
	v_add_f32_e32 v220, v220, v41
	v_cvt_pk_bf16_f32 v4, v34, v35
	v_cvt_pk_bf16_f32 v5, v36, v37
	v_cvt_pk_bf16_f32 v6, v38, v39
	v_cvt_pk_bf16_f32 v7, v40, v41
	s_nop 1
	s_setprio 1
	s_waitcnt lgkmcnt(12)
	v_mfma_f32_32x32x16_bf16 v[98:113], v[226:229], v[4:7], v[98:113]
	ds_read_b64_tr_b16 v[226:227], v17 offset:5120
	ds_read_b64_tr_b16 v[228:229], v17 offset:7168
	v_exp_f32_e32 v42, v42
	v_exp_f32_e32 v43, v43
	v_add_f32_e32 v220, v220, v42
	v_add_f32_e32 v220, v220, v43
	s_waitcnt lgkmcnt(12)
	v_mfma_f32_32x32x16_bf16 v[82:97], v[230:233], v[4:7], v[82:97]
	ds_read_b64_tr_b16 v[230:231], v16 offset:8192
	ds_read_b64_tr_b16 v[232:233], v16 offset:10240
	v_exp_f32_e32 v44, v44
	v_exp_f32_e32 v45, v45
	v_add_f32_e32 v220, v220, v44
	v_add_f32_e32 v220, v220, v45
	s_waitcnt lgkmcnt(12)
	v_mfma_f32_32x32x16_bf16 v[66:81], v[234:237], v[4:7], v[66:81]
	ds_read_b64_tr_b16 v[234:235], v17 offset:8192
	ds_read_b64_tr_b16 v[236:237], v17 offset:10240
	v_exp_f32_e32 v46, v46
	v_exp_f32_e32 v47, v47
	v_add_f32_e32 v220, v220, v46
	v_add_f32_e32 v220, v220, v47
	s_waitcnt lgkmcnt(12)
	v_mfma_f32_32x32x16_bf16 v[50:65], v[238:241], v[4:7], v[50:65]
	ds_read_b64_tr_b16 v[238:239], v16 offset:9216
	ds_read_b64_tr_b16 v[240:241], v16 offset:11264
	v_exp_f32_e32 v48, v48
	v_exp_f32_e32 v49, v49
	v_add_f32_e32 v220, v220, v48
	v_add_f32_e32 v220, v220, v49
	v_cvt_pk_bf16_f32 v8, v42, v43
	v_cvt_pk_bf16_f32 v9, v44, v45
	v_cvt_pk_bf16_f32 v10, v46, v47
	v_cvt_pk_bf16_f32 v11, v48, v49
	s_nop 1
	s_waitcnt lgkmcnt(12)
	v_mfma_f32_32x32x16_bf16 v[98:113], v[242:245], v[8:11], v[98:113]
	ds_read_b64_tr_b16 v[242:243], v17 offset:9216
	ds_read_b64_tr_b16 v[244:245], v17 offset:11264
	v_exp_f32_e32 v18, v18
	v_exp_f32_e32 v19, v19
	v_add_f32_e32 v220, v220, v18
	v_add_f32_e32 v220, v220, v19
	s_waitcnt lgkmcnt(12)
	v_mfma_f32_32x32x16_bf16 v[82:97], v[246:249], v[8:11], v[82:97]
	ds_read_b64_tr_b16 v[246:247], v16 offset:12288
	ds_read_b64_tr_b16 v[248:249], v16 offset:14336
	v_exp_f32_e32 v20, v20
	v_exp_f32_e32 v21, v21
	v_add_f32_e32 v220, v220, v20
	v_add_f32_e32 v220, v220, v21
	s_waitcnt lgkmcnt(12)
	v_mfma_f32_32x32x16_bf16 v[66:81], v[250:253], v[8:11], v[66:81]
	ds_read_b64_tr_b16 v[250:251], v17 offset:12288
	ds_read_b64_tr_b16 v[252:253], v17 offset:14336
	v_exp_f32_e32 v22, v22
	v_exp_f32_e32 v23, v23
	v_add_f32_e32 v220, v220, v22
	v_add_f32_e32 v220, v220, v23
	s_waitcnt lgkmcnt(12)
	v_mfma_f32_32x32x16_bf16 v[50:65], v[226:229], v[8:11], v[50:65]
	ds_read_b64_tr_b16 v[226:227], v16 offset:13312
	ds_read_b64_tr_b16 v[228:229], v16 offset:15360
	v_exp_f32_e32 v24, v24
	v_exp_f32_e32 v25, v25
	v_add_f32_e32 v220, v220, v24
	v_add_f32_e32 v220, v220, v25
	v_cvt_pk_bf16_f32 v12, v18, v19
	v_cvt_pk_bf16_f32 v13, v20, v21
	v_cvt_pk_bf16_f32 v14, v22, v23
	v_cvt_pk_bf16_f32 v15, v24, v25
	s_nop 1
	s_waitcnt lgkmcnt(12)
	v_mfma_f32_32x32x16_bf16 v[98:113], v[230:233], v[12:15], v[98:113]
	ds_read_b64_tr_b16 v[230:231], v17 offset:13312
	ds_read_b64_tr_b16 v[232:233], v17 offset:15360
	v_exp_f32_e32 v26, v26
	v_exp_f32_e32 v27, v27
	v_add_f32_e32 v220, v220, v26
	v_add_f32_e32 v220, v220, v27
	s_waitcnt lgkmcnt(12)
	v_mfma_f32_32x32x16_bf16 v[82:97], v[234:237], v[12:15], v[82:97]
	v_exp_f32_e32 v28, v28
	v_exp_f32_e32 v29, v29
	v_add_f32_e32 v220, v220, v28
	v_add_f32_e32 v220, v220, v29
	s_waitcnt lgkmcnt(10)
	v_mfma_f32_32x32x16_bf16 v[66:81], v[238:241], v[12:15], v[66:81]
	v_exp_f32_e32 v30, v30
	v_exp_f32_e32 v31, v31
	v_add_f32_e32 v220, v220, v30
	v_add_f32_e32 v220, v220, v31
	s_waitcnt lgkmcnt(8)
	v_mfma_f32_32x32x16_bf16 v[50:65], v[242:245], v[12:15], v[50:65]
	v_exp_f32_e32 v32, v32
	v_exp_f32_e32 v33, v33
	v_add_f32_e32 v220, v220, v32
	v_add_f32_e32 v220, v220, v33
	v_cvt_pk_bf16_f32 v222, v26, v27
	v_cvt_pk_bf16_f32 v223, v28, v29
	v_cvt_pk_bf16_f32 v224, v30, v31
	v_cvt_pk_bf16_f32 v225, v32, v33
	s_nop 1
	s_waitcnt lgkmcnt(6)
	v_mfma_f32_32x32x16_bf16 v[98:113], v[246:249], v[222:225], v[98:113]
	s_waitcnt lgkmcnt(4)
	v_mfma_f32_32x32x16_bf16 v[82:97], v[250:253], v[222:225], v[82:97]
	s_waitcnt lgkmcnt(2)
	v_mfma_f32_32x32x16_bf16 v[66:81], v[226:229], v[222:225], v[66:81]
	s_waitcnt lgkmcnt(0)
	v_mfma_f32_32x32x16_bf16 v[50:65], v[230:233], v[222:225], v[50:65]
	s_setprio 0
